# GEMM K-loop head at byte offset 16 mod 64 (placement experiment)
# speedup vs baseline: 1.0046x; 1.0046x over previous
; #define PG8_STAGE(bufoff, gbase, voff) do { _Pragma("unroll") for (int _i = 0; _i < 2; ++_i) \
;         __builtin_amdgcn_global_load_lds((const unsigned*)((const char*)(gbase) + (voff)[_i]), (LAS unsigned*)(lds + (bufoff) + ldsw + _i * 8192), 16, 0, 0); } while (0)
; #define PG8_LDA(dst, b, h) do { _Pragma("unroll") for (int m = 0; m < 4; ++m) _Pragma("unroll") for (int k = 0; k < 2; ++k) dst[m][k] = *(const LAS bf16x8*)(lds + PG8_SA(b, h) + aoff + m * 2048 + k * 1024); } while (0)
; #define PG8_LDB(dst, b, h) do { _Pragma("unroll") for (int n = 0; n < 2; ++n) _Pragma("unroll") for (int k = 0; k < 2; ++k) dst[n][k] = *(const LAS bf16x8*)(lds + PG8_SB(b, h) + boff + n * 2048 + k * 1024); } while (0)
; #define PG8_MMA(ai, bj, At, Bt) do { __builtin_amdgcn_s_setprio(1); _Pragma("unroll") for (int m = 0; m < 4; ++m) _Pragma("unroll") for (int n = 0; n < 2; ++n) _Pragma("unroll") for (int k = 0; k < 2; ++k) \
;         acc[ai][bj][m][n] = __builtin_amdgcn_mfma_f32_16x16x32_bf16(Bt[n][k], At[m][k], acc[ai][bj][m][n], 0, 0, 0); __builtin_amdgcn_s_setprio(0); } while (0)
; #define PG8_WAIT_V(n) asm volatile("s_waitcnt vmcnt(" #n ")" ::: "memory")
; #define PG8_WAIT_L(n) asm volatile("s_waitcnt lgkmcnt(" #n ")" ::: "memory")
; #define PG8_BAR __builtin_amdgcn_s_barrier()
; #define PG8_SCHED __builtin_amdgcn_sched_barrier(0)
; __device__ __forceinline__ void gemm_phase(LAS unsigned char* lds, const GemmP g, const EpiP e) {
;     ...
;         for (int t = 0; t < nt; t += 2) {
;             const bool last = (t == nt - 2);
;             const char* a1 = cA + (size_t)(t + 1) * kstepA;
;             const char* a2 = last ? nA : cA + (size_t)(t + 2) * kstepA; const char* b2 = last ? nB : cB + (size_t)(t + 2) * kstepB;
;             const char* a3 = a2 + kstepA; const char* b3 = b2 + kstepB;
;             PG8_LDB(B0, 0, 0); PG8_LDB(B1, 0, 1); PG8_SCHED; PG8_LDA(At, 0, 0); PG8_STAGE(PG8_SA(1, 1), a1 + hstepA, voffA);
;             PG8_WAIT_V(8); PG8_WAIT_L(0); PG8_BAR; PG8_MMA(0, 0, At, B0); PG8_MMA(0, 1, At, B1); PG8_BAR; PG8_SCHED;
;             PG8_LDA(At, 0, 1); PG8_STAGE(PG8_SB(0, 0), b2, voffB); PG8_STAGE(PG8_SB(0, 1), b2 + hstepB, voffB); PG8_STAGE(PG8_SA(0, 0), a2, voffA);
;             PG8_WAIT_V(8); PG8_WAIT_L(0); PG8_BAR; PG8_MMA(1, 0, At, B0); PG8_MMA(1, 1, At, B1); PG8_BAR; PG8_SCHED;
.LBB0_392:
	s_cmp_lt_i32 s69, 1
	s_cbranch_scc1 .LBB0_395
	s_add_u32 s24, s78, s90
	s_addc_u32 s25, s79, s7
	s_add_i32 s26, s69, -2
	s_add_u32 s27, s40, 0x100
	s_addc_u32 s28, s41, 0
	s_mov_b64 s[18:19], 0
	s_cmp_eq_u32 s99, 0
	s_cbranch_scc1 .LBB0_394
	s_mov_b32 s99, 0
	s_add_u32 s30, s18, 1
	s_addc_u32 s31, s19, 0
	s_add_u32 s16, s18, 2
	s_addc_u32 s17, s19, 0
	s_lshl_b64 s[20:21], s[16:17], s77
	s_add_u32 s19, s78, s20
	s_addc_u32 s20, s79, s21
	s_cmp_eq_u32 s26, s18
	s_cselect_b32 s21, s51, s20
	s_cselect_b32 s20, s50, s19
	s_cselect_b32 s22, s80, s27
	s_cselect_b32 s23, s81, s28
	s_add_u32 s18, s20, s38
	s_addc_u32 s19, s21, s39
	s_add_i32 s29, 0, 0x10000
	v_add_u32_e32 v96, s29, v179
	s_add_i32 s34, 0, 0x14000
	ds_read_b128 v[132:135], v96
	ds_read_b128 v[136:139], v96 offset:1024
	ds_read_b128 v[160:163], v96 offset:2048
	ds_read_b128 v[164:167], v96 offset:3072
	v_add_u32_e32 v96, s34, v179
	ds_read_b128 v[168:171], v96
	ds_read_b128 v[172:175], v96 offset:1024
	ds_read_b128 v[216:219], v96 offset:2048
	ds_read_b128 v[220:223], v96 offset:3072
	s_lshl_b64 s[30:31], s[30:31], s77
	s_add_u32 s30, s24, s30
	s_addc_u32 s31, s25, s31
	v_lshl_add_u64 v[98:99], s[30:31], 0, v[140:141]
	s_add_i32 m0, s92, 0xc000
	ds_read_b128 v[224:227], v188
	ds_read_b128 v[228:231], v188 offset:1024
	ds_read_b128 v[232:235], v188 offset:2048
	ds_read_b128 v[236:239], v188 offset:3072
	ds_read_b128 v[240:243], v188 offset:4096
	ds_read_b128 v[244:247], v188 offset:5120
	ds_read_b128 v[248:251], v188 offset:6144
	ds_read_b128 v[204:207], v188 offset:7168
	global_load_lds_dwordx4 v[98:99], off
	v_lshl_add_u64 v[98:99], s[30:31], 0, v[142:143]
	s_add_i32 m0, s92, 0xe000
	s_nop 0
	global_load_lds_dwordx4 v[98:99], off
	s_waitcnt vmcnt(24)
	s_waitcnt lgkmcnt(0)
	s_barrier
	s_setprio 1
	s_waitcnt lgkmcnt(0)
	v_mfma_f32_16x16x32_bf16 v[128:131], v[132:135], v[224:227], v[128:131]
	v_mfma_f32_16x16x32_bf16 v[124:127], v[160:163], v[224:227], v[124:127]
	v_mfma_f32_16x16x32_bf16 v[120:123], v[132:135], v[232:235], v[120:123]
	v_mfma_f32_16x16x32_bf16 v[116:119], v[160:163], v[232:235], v[116:119]
	v_mfma_f32_16x16x32_bf16 v[112:115], v[132:135], v[240:243], v[112:115]
	v_mfma_f32_16x16x32_bf16 v[108:111], v[160:163], v[240:243], v[108:111]
	v_mfma_f32_16x16x32_bf16 v[104:107], v[132:135], v[248:251], v[104:107]
	v_mfma_f32_16x16x32_bf16 v[98:101], v[160:163], v[248:251], v[100:103]
	v_mfma_f32_16x16x32_bf16 v[128:131], v[136:139], v[228:231], v[128:131]
	v_mfma_f32_16x16x32_bf16 v[124:127], v[164:167], v[228:231], v[124:127]
	v_mfma_f32_16x16x32_bf16 v[120:123], v[136:139], v[236:239], v[120:123]
	v_mfma_f32_16x16x32_bf16 v[116:119], v[164:167], v[236:239], v[116:119]
	v_mfma_f32_16x16x32_bf16 v[112:115], v[136:139], v[244:247], v[112:115]
	v_mfma_f32_16x16x32_bf16 v[108:111], v[164:167], v[244:247], v[108:111]
	v_mfma_f32_16x16x32_bf16 v[104:107], v[136:139], v[204:207], v[104:107]
	v_mfma_f32_16x16x32_bf16 v[98:101], v[164:167], v[204:207], v[98:101]
	s_setprio 0
	s_setprio 1
	v_mfma_f32_16x16x32_bf16 v[92:95], v[168:171], v[224:227], v[92:95]
	v_mfma_f32_16x16x32_bf16 v[88:91], v[216:219], v[224:227], v[88:91]
	v_mfma_f32_16x16x32_bf16 v[84:87], v[168:171], v[232:235], v[84:87]
	v_mfma_f32_16x16x32_bf16 v[80:83], v[216:219], v[232:235], v[80:83]
	v_mfma_f32_16x16x32_bf16 v[76:79], v[168:171], v[240:243], v[76:79]
	v_mfma_f32_16x16x32_bf16 v[72:75], v[216:219], v[240:243], v[72:75]
	v_mfma_f32_16x16x32_bf16 v[68:71], v[168:171], v[248:251], v[68:71]
	v_mfma_f32_16x16x32_bf16 v[64:67], v[216:219], v[248:251], v[64:67]
	v_mfma_f32_16x16x32_bf16 v[92:95], v[172:175], v[228:231], v[92:95]
	v_mfma_f32_16x16x32_bf16 v[88:91], v[220:223], v[228:231], v[88:91]
	v_mfma_f32_16x16x32_bf16 v[84:87], v[172:175], v[236:239], v[84:87]
	v_mfma_f32_16x16x32_bf16 v[80:83], v[220:223], v[236:239], v[80:83]
	v_mfma_f32_16x16x32_bf16 v[76:79], v[172:175], v[244:247], v[76:79]
	v_mfma_f32_16x16x32_bf16 v[72:75], v[220:223], v[244:247], v[72:75]
	v_mfma_f32_16x16x32_bf16 v[68:71], v[172:175], v[204:207], v[68:71]
	v_mfma_f32_16x16x32_bf16 v[64:67], v[220:223], v[204:207], v[64:67]
	s_setprio 0
	s_barrier
	s_add_i32 s29, s29, s91
	v_lshl_add_u64 v[176:177], s[22:23], 0, v[146:147]
	s_mov_b32 m0, s29
	ds_read_b128 v[204:207], v188 offset:16384
	ds_read_b128 v[224:227], v188 offset:17408
	ds_read_b128 v[228:231], v188 offset:18432
	ds_read_b128 v[232:235], v188 offset:19456
	ds_read_b128 v[236:239], v188 offset:20480
	ds_read_b128 v[240:243], v188 offset:21504
	ds_read_b128 v[244:247], v188 offset:22528
	ds_read_b128 v[248:251], v188 offset:23552
	global_load_lds_dwordx4 v[176:177], off
	s_add_i32 m0, s29, 0x2000
	v_lshl_add_u64 v[210:211], s[22:23], 0, v[144:145]
	s_add_u32 s22, s22, s48
	s_addc_u32 s23, s23, s49
	s_add_i32 s29, s34, s91
	global_load_lds_dwordx4 v[210:211], off
	v_lshl_add_u64 v[212:213], s[22:23], 0, v[146:147]
	s_mov_b32 m0, s29
	v_lshl_add_u64 v[190:191], s[22:23], 0, v[144:145]
	global_load_lds_dwordx4 v[212:213], off
	s_add_i32 m0, s29, 0x2000
	v_lshl_add_u64 v[102:103], s[20:21], 0, v[140:141]
	global_load_lds_dwordx4 v[190:191], off
	s_mov_b32 m0, s92
	s_nop 0
	global_load_lds_dwordx4 v[102:103], off
	v_lshl_add_u64 v[102:103], s[20:21], 0, v[142:143]
	s_mov_b32 m0, s93
	s_nop 0
	global_load_lds_dwordx4 v[102:103], off
	s_waitcnt vmcnt(24)
	s_waitcnt lgkmcnt(0)
	s_barrier
; #define PG8_STAGE(bufoff, gbase, voff) do { _Pragma("unroll") for (int _i = 0; _i < 2; ++_i) \
;         __builtin_amdgcn_global_load_lds((const unsigned*)((const char*)(gbase) + (voff)[_i]), (LAS unsigned*)(lds + (bufoff) + ldsw + _i * 8192), 16, 0, 0); } while (0)
; #define PG8_LDA(dst, b, h) do { _Pragma("unroll") for (int m = 0; m < 4; ++m) _Pragma("unroll") for (int k = 0; k < 2; ++k) dst[m][k] = *(const LAS bf16x8*)(lds + PG8_SA(b, h) + aoff + m * 2048 + k * 1024); } while (0)
; #define PG8_LDB(dst, b, h) do { _Pragma("unroll") for (int n = 0; n < 2; ++n) _Pragma("unroll") for (int k = 0; k < 2; ++k) dst[n][k] = *(const LAS bf16x8*)(lds + PG8_SB(b, h) + boff + n * 2048 + k * 1024); } while (0)
; #define PG8_MMA(ai, bj, At, Bt) do { __builtin_amdgcn_s_setprio(1); _Pragma("unroll") for (int m = 0; m < 4; ++m) _Pragma("unroll") for (int n = 0; n < 2; ++n) _Pragma("unroll") for (int k = 0; k < 2; ++k) \
;         acc[ai][bj][m][n] = __builtin_amdgcn_mfma_f32_16x16x32_bf16(Bt[n][k], At[m][k], acc[ai][bj][m][n], 0, 0, 0); __builtin_amdgcn_s_setprio(0); } while (0)
; #define PG8_WAIT_V(n) asm volatile("s_waitcnt vmcnt(" #n ")" ::: "memory")
; #define PG8_WAIT_L(n) asm volatile("s_waitcnt lgkmcnt(" #n ")" ::: "memory")
; #define PG8_BAR __builtin_amdgcn_s_barrier()
; #define PG8_SCHED __builtin_amdgcn_sched_barrier(0)
; __device__ __forceinline__ void gemm_phase(LAS unsigned char* lds, const GemmP g, const EpiP e) {
;     ...
;             PG8_WAIT_V(8); PG8_WAIT_L(0); PG8_BAR; PG8_MMA(1, 0, At, B0); PG8_MMA(1, 1, At, B1); PG8_BAR; PG8_SCHED;
;             PG8_LDB(B0, 1, 0); PG8_LDB(B1, 1, 1); PG8_SCHED; PG8_LDA(At, 1, 0); PG8_STAGE(PG8_SA(0, 1), a2 + hstepA, voffA);
;             PG8_WAIT_V(8); PG8_WAIT_L(0); PG8_BAR; PG8_MMA(0, 0, At, B0); PG8_MMA(0, 1, At, B1); PG8_BAR; PG8_SCHED;
	s_setprio 1
	s_waitcnt lgkmcnt(0)
	v_mfma_f32_16x16x32_bf16 v[60:63], v[132:135], v[204:207], v[60:63]
	v_mfma_f32_16x16x32_bf16 v[56:59], v[160:163], v[204:207], v[56:59]
	v_mfma_f32_16x16x32_bf16 v[52:55], v[132:135], v[228:231], v[52:55]
	v_mfma_f32_16x16x32_bf16 v[48:51], v[160:163], v[228:231], v[48:51]
	v_mfma_f32_16x16x32_bf16 v[44:47], v[132:135], v[236:239], v[44:47]
	v_mfma_f32_16x16x32_bf16 v[40:43], v[160:163], v[236:239], v[40:43]
	v_mfma_f32_16x16x32_bf16 v[36:39], v[132:135], v[244:247], v[36:39]
	v_mfma_f32_16x16x32_bf16 v[32:35], v[160:163], v[244:247], v[32:35]
	v_mfma_f32_16x16x32_bf16 v[60:63], v[136:139], v[224:227], v[60:63]
	v_mfma_f32_16x16x32_bf16 v[56:59], v[164:167], v[224:227], v[56:59]
	v_mfma_f32_16x16x32_bf16 v[52:55], v[136:139], v[232:235], v[52:55]
	v_mfma_f32_16x16x32_bf16 v[48:51], v[164:167], v[232:235], v[48:51]
	v_mfma_f32_16x16x32_bf16 v[44:47], v[136:139], v[240:243], v[44:47]
	v_mfma_f32_16x16x32_bf16 v[40:43], v[164:167], v[240:243], v[40:43]
	v_mfma_f32_16x16x32_bf16 v[36:39], v[136:139], v[248:251], v[36:39]
	v_mfma_f32_16x16x32_bf16 v[32:35], v[164:167], v[248:251], v[32:35]
	s_setprio 0
	s_setprio 1
	v_mfma_f32_16x16x32_bf16 v[28:31], v[168:171], v[204:207], v[28:31]
	v_mfma_f32_16x16x32_bf16 v[24:27], v[216:219], v[204:207], v[24:27]
	v_mfma_f32_16x16x32_bf16 v[20:23], v[168:171], v[228:231], v[20:23]
	v_mfma_f32_16x16x32_bf16 v[16:19], v[216:219], v[228:231], v[16:19]
	v_mfma_f32_16x16x32_bf16 v[12:15], v[168:171], v[236:239], v[12:15]
	v_mfma_f32_16x16x32_bf16 v[8:11], v[216:219], v[236:239], v[8:11]
	v_mfma_f32_16x16x32_bf16 v[4:7], v[168:171], v[244:247], v[4:7]
	v_mfma_f32_16x16x32_bf16 v[0:3], v[216:219], v[244:247], v[0:3]
	v_mfma_f32_16x16x32_bf16 v[28:31], v[172:175], v[224:227], v[28:31]
	v_mfma_f32_16x16x32_bf16 v[24:27], v[220:223], v[224:227], v[24:27]
	v_mfma_f32_16x16x32_bf16 v[20:23], v[172:175], v[232:235], v[20:23]
	v_mfma_f32_16x16x32_bf16 v[16:19], v[220:223], v[232:235], v[16:19]
	v_mfma_f32_16x16x32_bf16 v[12:15], v[172:175], v[240:243], v[12:15]
	v_mfma_f32_16x16x32_bf16 v[8:11], v[220:223], v[240:243], v[8:11]
	v_mfma_f32_16x16x32_bf16 v[4:7], v[172:175], v[248:251], v[4:7]
	v_mfma_f32_16x16x32_bf16 v[0:3], v[220:223], v[248:251], v[0:3]
	s_setprio 0
	s_barrier
	s_add_i32 s22, 0, 0x18000
	v_add_u32_e32 v96, s22, v179
	s_add_i32 s23, 0, 0x1c000
	ds_read_b128 v[132:135], v96
	ds_read_b128 v[136:139], v96 offset:1024
	ds_read_b128 v[160:163], v96 offset:2048
	ds_read_b128 v[164:167], v96 offset:3072
	v_add_u32_e32 v96, s23, v179
	ds_read_b128 v[168:171], v96
	ds_read_b128 v[172:175], v96 offset:1024
	ds_read_b128 v[204:207], v96 offset:2048
	ds_read_b128 v[216:219], v96 offset:3072
	s_add_u32 s20, s20, s90
	s_addc_u32 s21, s21, s7
	s_mov_b32 m0, s73
	v_lshl_add_u64 v[102:103], s[20:21], 0, v[140:141]
	ds_read_b128 v[220:223], v188 offset:32768
	ds_read_b128 v[224:227], v188 offset:33792
	ds_read_b128 v[228:231], v188 offset:34816
	ds_read_b128 v[232:235], v188 offset:35840
	ds_read_b128 v[236:239], v188 offset:36864
	ds_read_b128 v[240:243], v188 offset:37888
	ds_read_b128 v[244:247], v188 offset:38912
	ds_read_b128 v[248:251], v188 offset:39936
	global_load_lds_dwordx4 v[102:103], off
	v_lshl_add_u64 v[102:103], s[20:21], 0, v[142:143]
	s_mov_b32 m0, s4
	s_nop 0
	global_load_lds_dwordx4 v[102:103], off
	s_waitcnt vmcnt(8)
	s_waitcnt lgkmcnt(0)
	s_barrier
	s_setprio 1
	s_waitcnt lgkmcnt(0)
	v_mfma_f32_16x16x32_bf16 v[128:131], v[132:135], v[220:223], v[128:131]
	v_mfma_f32_16x16x32_bf16 v[124:127], v[160:163], v[220:223], v[124:127]
	v_mfma_f32_16x16x32_bf16 v[120:123], v[132:135], v[228:231], v[120:123]
	v_mfma_f32_16x16x32_bf16 v[116:119], v[160:163], v[228:231], v[116:119]
	v_mfma_f32_16x16x32_bf16 v[112:115], v[132:135], v[236:239], v[112:115]
	v_mfma_f32_16x16x32_bf16 v[108:111], v[160:163], v[236:239], v[108:111]
	v_mfma_f32_16x16x32_bf16 v[102:105], v[132:135], v[244:247], v[104:107]
	v_mfma_f32_16x16x32_bf16 v[98:101], v[160:163], v[244:247], v[98:101]
	v_mfma_f32_16x16x32_bf16 v[128:131], v[136:139], v[224:227], v[128:131]
	v_mfma_f32_16x16x32_bf16 v[124:127], v[164:167], v[224:227], v[124:127]
	v_mfma_f32_16x16x32_bf16 v[120:123], v[136:139], v[232:235], v[120:123]
	v_mfma_f32_16x16x32_bf16 v[116:119], v[164:167], v[232:235], v[116:119]
	v_mfma_f32_16x16x32_bf16 v[112:115], v[136:139], v[240:243], v[112:115]
	v_mfma_f32_16x16x32_bf16 v[108:111], v[164:167], v[240:243], v[108:111]
	v_mfma_f32_16x16x32_bf16 v[104:107], v[136:139], v[248:251], v[102:105]
	v_mfma_f32_16x16x32_bf16 v[100:103], v[164:167], v[248:251], v[98:101]
	s_setprio 0
	s_setprio 1
	v_mfma_f32_16x16x32_bf16 v[92:95], v[168:171], v[220:223], v[92:95]
	v_mfma_f32_16x16x32_bf16 v[88:91], v[204:207], v[220:223], v[88:91]
	v_mfma_f32_16x16x32_bf16 v[84:87], v[168:171], v[228:231], v[84:87]
	v_mfma_f32_16x16x32_bf16 v[80:83], v[204:207], v[228:231], v[80:83]
	v_mfma_f32_16x16x32_bf16 v[76:79], v[168:171], v[236:239], v[76:79]
	v_mfma_f32_16x16x32_bf16 v[72:75], v[204:207], v[236:239], v[72:75]
	v_mfma_f32_16x16x32_bf16 v[68:71], v[168:171], v[244:247], v[68:71]
	v_mfma_f32_16x16x32_bf16 v[64:67], v[204:207], v[244:247], v[64:67]
	v_mfma_f32_16x16x32_bf16 v[92:95], v[172:175], v[224:227], v[92:95]
	v_mfma_f32_16x16x32_bf16 v[88:91], v[216:219], v[224:227], v[88:91]
	v_mfma_f32_16x16x32_bf16 v[84:87], v[172:175], v[232:235], v[84:87]
	v_mfma_f32_16x16x32_bf16 v[80:83], v[216:219], v[232:235], v[80:83]
	v_mfma_f32_16x16x32_bf16 v[76:79], v[172:175], v[240:243], v[76:79]
	v_mfma_f32_16x16x32_bf16 v[72:75], v[216:219], v[240:243], v[72:75]
	v_mfma_f32_16x16x32_bf16 v[68:71], v[172:175], v[248:251], v[68:71]
	v_mfma_f32_16x16x32_bf16 v[64:67], v[216:219], v[248:251], v[64:67]
	s_setprio 0
	s_barrier
; #define PG8_STAGE(bufoff, gbase, voff) do { _Pragma("unroll") for (int _i = 0; _i < 2; ++_i) \
;         __builtin_amdgcn_global_load_lds((const unsigned*)((const char*)(gbase) + (voff)[_i]), (LAS unsigned*)(lds + (bufoff) + ldsw + _i * 8192), 16, 0, 0); } while (0)
; #define PG8_LDA(dst, b, h) do { _Pragma("unroll") for (int m = 0; m < 4; ++m) _Pragma("unroll") for (int k = 0; k < 2; ++k) dst[m][k] = *(const LAS bf16x8*)(lds + PG8_SA(b, h) + aoff + m * 2048 + k * 1024); } while (0)
; #define PG8_MMA(ai, bj, At, Bt) do { __builtin_amdgcn_s_setprio(1); _Pragma("unroll") for (int m = 0; m < 4; ++m) _Pragma("unroll") for (int n = 0; n < 2; ++n) _Pragma("unroll") for (int k = 0; k < 2; ++k) \
;         acc[ai][bj][m][n] = __builtin_amdgcn_mfma_f32_16x16x32_bf16(Bt[n][k], At[m][k], acc[ai][bj][m][n], 0, 0, 0); __builtin_amdgcn_s_setprio(0); } while (0)
; #define PG8_WAIT_V(n) asm volatile("s_waitcnt vmcnt(" #n ")" ::: "memory")
; #define PG8_WAIT_L(n) asm volatile("s_waitcnt lgkmcnt(" #n ")" ::: "memory")
; #define PG8_BAR __builtin_amdgcn_s_barrier()
; #define PG8_SCHED __builtin_amdgcn_sched_barrier(0)
; __device__ __forceinline__ void gemm_phase(LAS unsigned char* lds, const GemmP g, const EpiP e) {
;     ...
;             PG8_LDA(At, 1, 1); PG8_STAGE(PG8_SB(1, 0), b3, voffB); PG8_STAGE(PG8_SB(1, 1), b3 + hstepB, voffB); PG8_STAGE(PG8_SA(1, 0), a3, voffA);
;             PG8_WAIT_V(8); PG8_WAIT_L(0); PG8_BAR; PG8_MMA(1, 0, At, B0); PG8_MMA(1, 1, At, B1); PG8_BAR; PG8_SCHED;
;         }
	s_add_i32 s20, s22, s91
	v_lshl_add_u64 v[98:99], v[176:177], 0, s[96:97]
	s_mov_b32 m0, s20
	ds_read_b128 v[220:223], v188 offset:49152
	ds_read_b128 v[224:227], v188 offset:50176
	ds_read_b128 v[228:231], v188 offset:51200
	ds_read_b128 v[232:235], v188 offset:52224
	ds_read_b128 v[236:239], v188 offset:53248
	ds_read_b128 v[240:243], v188 offset:54272
	ds_read_b128 v[244:247], v188 offset:55296
	ds_read_b128 v[248:251], v188 offset:56320
	global_load_lds_dwordx4 v[98:99], off
	v_lshl_add_u64 v[98:99], v[210:211], 0, s[96:97]
	s_add_i32 m0, s20, 0x2000
	s_add_i32 s20, s23, s91
	global_load_lds_dwordx4 v[98:99], off
	v_lshl_add_u64 v[98:99], v[212:213], 0, s[96:97]
	s_mov_b32 m0, s20
	s_nop 0
	global_load_lds_dwordx4 v[98:99], off
	v_lshl_add_u64 v[98:99], v[190:191], 0, s[96:97]
	s_add_i32 m0, s20, 0x2000
	s_nop 0
	global_load_lds_dwordx4 v[98:99], off
	v_lshl_add_u64 v[98:99], s[18:19], 0, v[140:141]
	s_mov_b32 m0, s5
	s_nop 0
	global_load_lds_dwordx4 v[98:99], off
	v_lshl_add_u64 v[98:99], s[18:19], 0, v[142:143]
	s_mov_b32 m0, s44
	s_nop 0
	global_load_lds_dwordx4 v[98:99], off
	s_waitcnt vmcnt(8)
	s_waitcnt lgkmcnt(0)
	s_barrier
	s_setprio 1
	s_waitcnt lgkmcnt(0)
	v_mfma_f32_16x16x32_bf16 v[60:63], v[132:135], v[220:223], v[60:63]
	v_mfma_f32_16x16x32_bf16 v[56:59], v[160:163], v[220:223], v[56:59]
	v_mfma_f32_16x16x32_bf16 v[52:55], v[132:135], v[228:231], v[52:55]
	v_mfma_f32_16x16x32_bf16 v[48:51], v[160:163], v[228:231], v[48:51]
	v_mfma_f32_16x16x32_bf16 v[44:47], v[132:135], v[236:239], v[44:47]
	v_mfma_f32_16x16x32_bf16 v[40:43], v[160:163], v[236:239], v[40:43]
	v_mfma_f32_16x16x32_bf16 v[36:39], v[132:135], v[244:247], v[36:39]
	v_mfma_f32_16x16x32_bf16 v[32:35], v[160:163], v[244:247], v[32:35]
	v_mfma_f32_16x16x32_bf16 v[60:63], v[136:139], v[224:227], v[60:63]
	v_mfma_f32_16x16x32_bf16 v[56:59], v[164:167], v[224:227], v[56:59]
	v_mfma_f32_16x16x32_bf16 v[52:55], v[136:139], v[232:235], v[52:55]
	v_mfma_f32_16x16x32_bf16 v[48:51], v[164:167], v[232:235], v[48:51]
	v_mfma_f32_16x16x32_bf16 v[44:47], v[136:139], v[240:243], v[44:47]
	v_mfma_f32_16x16x32_bf16 v[40:43], v[164:167], v[240:243], v[40:43]
	v_mfma_f32_16x16x32_bf16 v[36:39], v[136:139], v[248:251], v[36:39]
	v_mfma_f32_16x16x32_bf16 v[32:35], v[164:167], v[248:251], v[32:35]
	s_setprio 0
	s_setprio 1
	v_mfma_f32_16x16x32_bf16 v[28:31], v[168:171], v[220:223], v[28:31]
	v_mfma_f32_16x16x32_bf16 v[24:27], v[204:207], v[220:223], v[24:27]
	v_mfma_f32_16x16x32_bf16 v[20:23], v[168:171], v[228:231], v[20:23]
	v_mfma_f32_16x16x32_bf16 v[16:19], v[204:207], v[228:231], v[16:19]
	v_mfma_f32_16x16x32_bf16 v[12:15], v[168:171], v[236:239], v[12:15]
	v_mfma_f32_16x16x32_bf16 v[8:11], v[204:207], v[236:239], v[8:11]
	v_mfma_f32_16x16x32_bf16 v[4:7], v[168:171], v[244:247], v[4:7]
	v_mfma_f32_16x16x32_bf16 v[0:3], v[204:207], v[244:247], v[0:3]
	v_mfma_f32_16x16x32_bf16 v[28:31], v[172:175], v[224:227], v[28:31]
	v_mfma_f32_16x16x32_bf16 v[24:27], v[216:219], v[224:227], v[24:27]
	v_mfma_f32_16x16x32_bf16 v[20:23], v[172:175], v[232:235], v[20:23]
	v_mfma_f32_16x16x32_bf16 v[16:19], v[216:219], v[232:235], v[16:19]
	v_mfma_f32_16x16x32_bf16 v[12:15], v[172:175], v[240:243], v[12:15]
	v_mfma_f32_16x16x32_bf16 v[8:11], v[216:219], v[240:243], v[8:11]
	v_mfma_f32_16x16x32_bf16 v[4:7], v[172:175], v[248:251], v[4:7]
	v_mfma_f32_16x16x32_bf16 v[0:3], v[216:219], v[248:251], v[0:3]
	s_setprio 0
	s_barrier
	s_add_u32 s27, s27, 0x100
	s_addc_u32 s28, s28, 0
	s_cmp_ge_i32 s16, s69
	s_mov_b64 s[18:19], s[16:17]
	s_cbranch_scc0 .LBB0_394
	s_branch .LBB0_395
	.p2align 6
	s_nop 0
	s_nop 0
	s_nop 0
	s_nop 0
